# speedup vs baseline: 1.0099x; 1.0099x over previous
; __device__ __forceinline__ const bf16* p32(const bf16* base, unsigned elem_off) { return (const bf16*)((const char*)base + (size_t)(elem_off * 2u)); }
; __device__ __forceinline__ float gate_of(const Params& p, const LaneId& L, int b) { return sigmoid_f(ldbf(p32(p.P, (unsigned)(L.tq * LDP + C_GT + L.h * 3 + b)))); }
; __device__ __forceinline__ void park_o(const f32x16* o, char* pk, int lane) {
; #pragma unroll
;   for (int d0 = 0; d0 < 4; ++d0)
; #pragma unroll
;     for (int a = 0; a < 4; ++a) { u32x2 w = {cvtpk(o[d0][4 * a], o[d0][4 * a + 1]), cvtpk(o[d0][4 * a + 2], o[d0][4 * a + 3])};
;       *reinterpret_cast<u32x2*>(pk + ((d0 * 4 + a) * 64 + lane) * 8) = w; }
; __device__ void nsa_item(const Params& p, int qb, int g, char* smem) {
;     ...
;   nsel = __builtin_amdgcn_readfirstlane(nsel);
;   {
;     const LaneId L = lane_id(q0, g);
;     park_o(o, smem + NSA_IMP + L.wid * 8192, L.lane);
; #pragma unroll
;     for (int d0 = 0; d0 < 4; ++d0) o[d0] = f32x16{};
;     { const unsigned qo = (unsigned)(L.tq * LDP + C_Q + L.h * 128 + L.hi * 8);
; #pragma unroll
;       for (int d0 = 0; d0 < 8; ++d0) qr[d0] = ld8(p32(p.P, qo + d0 * 16)); }
;     nsa_single<1>(p, L, q0, g, nsel, 0, smem, qr, gate_of(p, L, 1), o);
.LBB0_312:
	s_or_b64 exec, exec, s[8:9]
	v_add_u32_e32 v2, v73, v72
	v_add_u32_e32 v2, v2, v74
	v_add_u32_e32 v2, v2, v75
	v_add_u32_e32 v2, v2, v68
	v_mov_b32_e32 v145, v1
	v_add_u32_e32 v2, v2, v69
	s_waitcnt lgkmcnt(0)
	s_barrier
	v_cvt_pk_bf16_f32 v4, v4, v5
	v_ashrrev_i32_e32 v69, 6, v145
	v_and_b32_e32 v143, 63, v145
	v_lshl_add_u32 v141, v69, 13, v179
	v_lshlrev_b32_e32 v142, 3, v143
	v_cvt_pk_bf16_f32 v5, v6, v7
	v_or_b32_e32 v72, v141, v142
	v_cvt_pk_bf16_f32 v6, v8, v9
	v_cvt_pk_bf16_f32 v7, v10, v11
	ds_write2st64_b64 v72, v[4:5], v[6:7] offset1:1
	v_cvt_pk_bf16_f32 v4, v12, v13
	v_cvt_pk_bf16_f32 v5, v14, v15
	v_cvt_pk_bf16_f32 v6, v16, v17
	v_cvt_pk_bf16_f32 v7, v18, v19
	ds_write2st64_b64 v72, v[4:5], v[6:7] offset0:2 offset1:3
	v_cvt_pk_bf16_f32 v4, v52, v53
	v_cvt_pk_bf16_f32 v5, v54, v55
	v_cvt_pk_bf16_f32 v6, v56, v57
	v_cvt_pk_bf16_f32 v7, v58, v59
	s_addk_i32 s0, 0xff20
	ds_write2st64_b64 v72, v[4:5], v[6:7] offset0:4 offset1:5
	v_cvt_pk_bf16_f32 v4, v60, v61
	v_cvt_pk_bf16_f32 v5, v62, v63
	v_cvt_pk_bf16_f32 v6, v64, v65
	v_cvt_pk_bf16_f32 v7, v66, v67
	s_lshl_b32 s0, -1, s0
	ds_write2st64_b64 v72, v[4:5], v[6:7] offset0:6 offset1:7
	v_cvt_pk_bf16_f32 v4, v36, v37
	v_cvt_pk_bf16_f32 v5, v38, v39
	v_cvt_pk_bf16_f32 v6, v40, v41
	v_cvt_pk_bf16_f32 v7, v42, v43
	s_cmpk_gt_i32 s61, 0x383f
	ds_write2st64_b64 v72, v[4:5], v[6:7] offset0:8 offset1:9
	v_cvt_pk_bf16_f32 v4, v44, v45
	v_cvt_pk_bf16_f32 v5, v46, v47
	v_cvt_pk_bf16_f32 v6, v48, v49
	v_cvt_pk_bf16_f32 v7, v50, v51
	s_cselect_b32 s0, s0, -1
	ds_write2st64_b64 v72, v[4:5], v[6:7] offset0:10 offset1:11
	v_cvt_pk_bf16_f32 v4, v20, v21
	v_cvt_pk_bf16_f32 v5, v22, v23
	v_cvt_pk_bf16_f32 v6, v24, v25
	v_cvt_pk_bf16_f32 v7, v26, v27
	v_and_b32_e32 v68, s0, v71
	ds_write2st64_b64 v72, v[4:5], v[6:7] offset0:12 offset1:13
	v_cvt_pk_bf16_f32 v4, v28, v29
	v_cvt_pk_bf16_f32 v5, v30, v31
	v_cvt_pk_bf16_f32 v6, v32, v33
	v_cvt_pk_bf16_f32 v7, v34, v35
	v_bcnt_u32_b32 v68, v68, 0
	v_lshl_add_u32 v71, v69, 3, s5
	ds_write2st64_b64 v72, v[4:5], v[6:7] offset0:14 offset1:15
	v_bfe_u32 v6, v145, 2, 3
	v_add_u32_e32 v2, v2, v68
	v_or_b32_e32 v148, v71, v6
	v_add_u32_e32 v2, v2, v70
	v_bfe_u32 v68, v145, 5, 1
	v_and_or_b32 v70, v145, 3, s17
	v_mul_lo_u32 v7, v148, s33
	v_lshlrev_b32_e32 v5, 4, v68
	v_lshl_add_u32 v7, v70, 8, v7
	v_or_b32_e32 v7, v7, v5
	global_load_dwordx4 v[100:103], v7, s[46:47]
	global_load_dwordx4 v[104:107], v7, s[46:47] offset:32
	global_load_dwordx4 v[108:111], v7, s[46:47] offset:64
	global_load_dwordx4 v[112:115], v7, s[46:47] offset:96
	global_load_dwordx4 v[116:119], v7, s[46:47] offset:128
	global_load_dwordx4 v[120:123], v7, s[46:47] offset:160
	global_load_dwordx4 v[124:127], v7, s[46:47] offset:192
	global_load_dwordx4 v[128:131], v7, s[46:47] offset:224
	s_movk_i32 s25, 0x3100
	v_readfirstlane_b32 s0, v2
	v_mul_lo_u32 v2, v148, s25
	v_mad_u64_u32 v[8:9], s[2:3], v70, 3, v[2:3]
	v_lshl_add_u32 v2, v8, 1, v188
	global_load_ushort v144, v2, s[46:47]
	v_and_b32_e32 v4, 31, v145
	v_lshl_add_u32 v2, v69, 7, v189
	s_cmp_lt_i32 s0, 1
	v_cmp_gt_u32_e64 s[8:9], 32, v143
	v_lshl_add_u32 v147, v4, 2, v2
	v_lshl_add_u32 v146, v68, 4, v2
	s_cbranch_scc1 .LBB0_336
; __device__ __forceinline__ int v_rd_base(int lane) { return ((lane & 3) << 3) | (((lane >> 2) & 3) << 6) | (((lane >> 4) & 1) << 5) | (((lane >> 5) & 1) << 8); }
; template <int MODE>
; __device__ __forceinline__ void nsa_single(const Params& p, const LaneId& L, int q0, int g, int ntiles, int first, char* smem, const bf16x8* qr, float gate, f32x16* o) {
;     ...
;   const bf16* Kg; const bf16* Vg; const int ld = 128;
;   if (MODE == 1) { Kg = p.kvh + (long)(0 + g) * T * 128; Vg = p.kvh + (long)(4 + g) * T * 128; }
;   else { Kg = p.kvh + (long)(8 + g) * T * 128; Vg = p.kvh + (long)(12 + g) * T * 128; }
;   auto tile_row = [&](int i) -> int { const int ii = ntiles - 1 - i; if (MODE == 1) return __builtin_amdgcn_readfirstlane((int)ulist[ii]) * 64; return q0 - 512 + 64 * (first + ii); };
;   const int vb0 = (int)(uintptr_t)(smem + NSA_V0) + v_rd_base(L.lane);
;   float m = -1e30f, l = 0.f;
;   if (ntiles > 0) { const int row = tile_row(0); dma_k(Kg + (long)row * ld, ld, smem + NSA_K0, L.tid); dma_v(Vg + (long)row * ld, ld, smem + NSA_V0, L.tid); }
	s_lshl_b64 s[2:3], s[96:97], 22
	s_add_u32 s1, s34, s2
	s_addc_u32 s24, s35, s3
	s_sub_i32 s18, 7, s16
	s_lshl_b64 s[2:3], s[18:19], 22
	s_add_u32 s18, s34, s2
	s_addc_u32 s25, s35, s3
	s_add_i32 s2, s0, 0x20c1f
	v_mov_b32_e32 v2, s2
	ds_read_u8 v2, v2
	v_lshrrev_b32_e32 v8, 5, v145
	v_and_b32_e32 v7, 15, v145
	v_and_b32_e32 v9, 8, v8
	v_readfirstlane_b32 s12, v145
	s_waitcnt lgkmcnt(0)
	v_readfirstlane_b32 s2, v2
	v_ashrrev_i32_e32 v2, 4, v145
	v_and_b32_e32 v10, 7, v2
	v_bitop3_b32 v10, v10, v7, v9 bitop3:0x36
	v_lshlrev_b32_e32 v2, 8, v2
	v_lshl_or_b32 v2, v10, 4, v2
	v_add_u32_e32 v10, 0x200, v145
	s_lshl_b32 s2, s2, 6
	v_ashrrev_i32_e32 v10, 4, v10
	s_ashr_i32 s3, s2, 31
	v_and_b32_e32 v11, 7, v10
	s_lshl_b64 s[2:3], s[2:3], 8
	v_bitop3_b32 v7, v11, v7, v9 bitop3:0x36
	v_lshlrev_b32_e32 v9, 8, v10
	s_add_u32 s10, s1, s2
	v_lshl_or_b32 v132, v7, 4, v9
	v_and_b32_e32 v7, 0x60, v145
	v_lshlrev_b32_e32 v9, 3, v145
	s_addc_u32 s11, s24, s3
	s_lshl_b32 s12, s12, 4
	v_and_or_b32 v7, v9, 24, v7
	v_bfe_u32 v9, v145, 2, 2
	s_and_b32 s12, s12, 0xfffffc00
	v_and_or_b32 v8, v8, 4, v9
	v_lshrrev_b32_e32 v9, 4, v145
	v_lshrrev_b32_e32 v10, 1, v145
	s_mov_b32 m0, s12
	v_and_b32_e32 v9, 48, v9
	v_and_b32_e32 v10, 8, v10
	global_load_lds_dwordx4 v2, s[10:11]
	s_add_i32 m0, s12, 0x2000
	v_or3_b32 v8, v8, v9, v10
	s_add_u32 s2, s18, s2
	v_lshlrev_b32_e32 v8, 8, v8
	v_lshlrev_b32_e32 v7, 1, v7
	global_load_lds_dwordx4 v132, s[10:11]
	s_addc_u32 s3, s25, s3
	v_or_b32_e32 v134, v8, v7
	s_add_i32 m0, s12, 0x8000
	s_movk_i32 s10, 0x2000
	global_load_lds_dwordx4 v134, s[2:3]
	v_bitop3_b32 v136, v8, s10, v7 bitop3:0x36
	s_add_i32 m0, s12, 0xa000
	v_add_u32_e32 v7, 1, v70
	global_load_lds_dwordx4 v136, s[2:3]
	v_cvt_f32_u32_e32 v7, v7
	s_mov_b32 s2, 0xc2fc0000
	v_lshlrev_b32_e32 v152, 8, v4
	v_and_or_b32 v4, v145, 7, v10
	v_mul_f32_e32 v8, -0.5, v7
	v_cmp_gt_f32_e32 vcc, s2, v8
	v_lshlrev_b32_e32 v4, 4, v4
	s_movk_i32 s2, 0x60
	v_cndmask_b32_e32 v8, 0, v180, vcc
	v_fmac_f32_e32 v8, -0.5, v7
	v_exp_f32_e32 v7, v8
	v_bitop3_b32 v156, v4, v5, s2 bitop3:0x1e
	s_movk_i32 s2, 0x80
	v_cndmask_b32_e32 v8, 0, v181, vcc
	v_lshlrev_b32_e32 v6, 5, v6
	v_bitop3_b32 v157, v4, v5, s2 bitop3:0x1e
	s_movk_i32 s2, 0xa0
	v_ldexp_f32 v7, v7, v8
	v_lshl_or_b32 v6, v69, 8, v6
	v_bitop3_b32 v158, v4, v5, s2 bitop3:0x1e
	s_movk_i32 s2, 0xc0
	v_mul_f32_e32 v138, 0x3fb8aa3b, v7
	v_add_u32_e32 v149, 0x20400, v6
	v_lshlrev_b32_e32 v6, 1, v143
	v_lshlrev_b32_e32 v7, 4, v143
	v_and_b32_e32 v8, 0x118, v142
	v_lshlrev_b32_e32 v150, 2, v68
	v_bitop3_b32 v159, v4, v5, s2 bitop3:0x1e
	s_movk_i32 s2, 0xe0
	v_and_b32_e32 v7, 0xc0, v7
	v_cvt_f32_ubyte0_e32 v9, v150
	v_xor_b32_e32 v153, v4, v5
	v_bitop3_b32 v154, v4, v5, 32 bitop3:0x1e
	v_bitop3_b32 v155, v4, v5, 64 bitop3:0x1e
	v_bitop3_b32 v160, v4, v5, s2 bitop3:0x1e
	v_and_or_b32 v4, v6, 32, v8
	v_mov_b32_e32 v52, v3
	v_mov_b32_e32 v53, v3
	v_mul_f32_e32 v151, v138, v9
	v_or3_b32 v161, v7, v4, s23
	v_mov_b32_e32 v54, v3
	v_mov_b32_e32 v55, v3
	v_mov_b32_e32 v56, v3
	v_mov_b32_e32 v57, v3
	v_mov_b32_e32 v58, v3
	v_mov_b32_e32 v59, v3
	v_mov_b32_e32 v60, v3
	v_mov_b32_e32 v61, v3
	v_mov_b32_e32 v62, v3
	v_mov_b32_e32 v63, v3
	v_mov_b32_e32 v64, v3
	v_mov_b32_e32 v65, v3
	v_mov_b32_e32 v66, v3
	v_mov_b32_e32 v67, v3
	v_mov_b64_e32 v[36:37], v[52:53]
	v_mov_b64_e32 v[20:21], v[52:53]
	v_mov_b64_e32 v[4:5], v[52:53]
	s_mov_b32 s61, 1
	s_mov_b32 s97, 0
	v_mov_b32_e32 v133, v3
	v_mov_b32_e32 v135, v3
	v_mov_b32_e32 v137, v3
	v_mov_b32_e32 v139, v138
	v_mov_b32_e32 v162, 0
	v_mov_b32_e32 v165, 0xf149f2ca
	s_mov_b32 s26, s0
	v_mov_b64_e32 v[38:39], v[54:55]
	v_mov_b64_e32 v[40:41], v[56:57]
	v_mov_b64_e32 v[42:43], v[58:59]
	v_mov_b64_e32 v[44:45], v[60:61]
	v_mov_b64_e32 v[46:47], v[62:63]
	v_mov_b64_e32 v[48:49], v[64:65]
	v_mov_b64_e32 v[50:51], v[66:67]
	v_mov_b64_e32 v[22:23], v[54:55]
	v_mov_b64_e32 v[24:25], v[56:57]
	v_mov_b64_e32 v[26:27], v[58:59]
	v_mov_b64_e32 v[28:29], v[60:61]
	v_mov_b64_e32 v[30:31], v[62:63]
	v_mov_b64_e32 v[32:33], v[64:65]
	v_mov_b64_e32 v[34:35], v[66:67]
	v_mov_b64_e32 v[6:7], v[54:55]
	v_mov_b64_e32 v[8:9], v[56:57]
	v_mov_b64_e32 v[10:11], v[58:59]
	v_mov_b64_e32 v[12:13], v[60:61]
	v_mov_b64_e32 v[14:15], v[62:63]
	v_mov_b64_e32 v[16:17], v[64:65]
	v_mov_b64_e32 v[18:19], v[66:67]
	s_waitcnt vmcnt(0)
	v_mov_b32_e32 v226, 0
	v_mul_f32_e32 v227, 0x40faf232, v138
	v_mul_f32_e32 v228, 0x417af232, v138
	v_mul_f32_e32 v229, 0x41bc35a6, v138
	v_mul_f32_e32 v230, 0x427af232, v138
	v_mul_f32_e32 v231, 0x428d283c, v138
	v_mul_f32_e32 v232, 0x429cd760, v138
	v_mul_f32_e32 v233, 0x42ac8683, v138
	v_mul_f32_e32 v234, 0x42faf232, v138
	v_mul_f32_e32 v235, 0x430550ab, v138
	v_mul_f32_e32 v236, 0x430d283c, v138
	v_mul_f32_e32 v237, 0x4314ffce, v138
	v_mul_f32_e32 v238, 0x433c35a6, v138
	v_mul_f32_e32 v239, 0x43440d37, v138
	v_mul_f32_e32 v240, 0x434be4c9, v138
	v_mul_f32_e32 v241, 0x4353bc5b, v138
	s_branch .LBB0_316

; #define KSWZ(row, colB) ((row) * 256 + ((colB) ^ (KSWZF(row) << 4)))
; #define SBAR() __builtin_amdgcn_sched_barrier(0)
; template <int H> __device__ __forceinline__ void qkt_half(f32x16& pz, const char* Ks, const bf16x8* qr, int r32, int hi) {
;   bf16x8 kf[8];
; #pragma unroll
;   for (int d0 = 0; d0 < 8; ++d0) { const int cb = (d0 * 16 + hi * 8) * 2; kf[d0] = *reinterpret_cast<const bf16x8*>(Ks + KSWZ(32 * H + r32, cb)); }
;   asm volatile("s_waitcnt lgkmcnt(0)" ::: "memory"); SBAR();
;   f32x16 pb = {};
; #pragma unroll
;   for (int d0 = 0; d0 < 8; d0 += 2) {
;     pz = __builtin_amdgcn_mfma_f32_32x32x16_bf16(kf[d0], qr[d0], pz, 0, 0, 0);
;     pb = __builtin_amdgcn_mfma_f32_32x32x16_bf16(kf[d0 + 1], qr[d0 + 1], pb, 0, 0, 0); }
; template <int MODE>
; __device__ __forceinline__ void nsa_single(const Params& p, const LaneId& L, int q0, int g, int ntiles, int first, char* smem, const bf16x8* qr, float gate, f32x16* o) {
;     ...
;     int pb = row, lo, hl; float badd = 0.f;
;     if (MODE == 1) { const int j = row >> 6; lo = NEG; const bool fl = ((mysel[j >> 5] >> (j & 31)) & 1u) != 0u;
;       if (row == q0) hl = fl ? (L.tq - pb) : NEG; else { hl = 1000; badd = fl ? 0.f : -INFINITY; } }
;     else { lo = L.tq - 512 - pb; hl = L.tq - pb; }
;     constexpr float C = 0.08838834764831845f * LOG2E;
;     const float A1 = L.sl2; const float B1 = L.sl2 * (float)(pb - L.tq) + A1 * (float)(4 * L.hi) + badd;
;     const int lo2 = lo - 4 * L.hi, hl2 = hl - 4 * L.hi;
;     const bool nomask = __all(lo2 < 0 && hl2 >= 63);
.LBB0_318:
	s_ashr_i32 s3, s2, 5
	v_lshl_add_u32 v68, s3, 2, v149
	ds_read_b32 v72, v68
	s_lshl_b32 s3, s2, 6
	s_and_b32 s2, s2, 31
	v_sub_u32_e32 v74, s3, v148
	v_cvt_f32_i32_e32 v74, v74
	s_waitcnt lgkmcnt(0)
	v_bfe_u32 v72, v72, s2, 1
	s_cmp_eq_u32 s3, s5
	v_subrev_u32_e32 v73, s3, v148
	v_cmp_eq_u32_e32 vcc, 0, v72
	v_fma_f32 v74, v138, v74, v151
	s_nop 1
	v_cndmask_b32_e32 v72, v73, v190, vcc
	v_cndmask_b32_e32 v73, 0, v183, vcc
	s_cselect_b64 vcc, -1, 0
	v_cndmask_b32_e32 v72, v191, v72, vcc
	v_cndmask_b32_e64 v73, v73, 0, vcc
	v_sub_u32_e32 v163, v72, v150
	v_add_f32_e32 v140, v74, v73
	v_cmp_lt_i32_e32 vcc, 62, v163
	s_nop 3
	s_cmp_lg_u64 vcc, exec
	s_cselect_b64 s[98:99], -1, 0
	v_add_u32_e32 v248, s22, v152
	v_add_u32_e32 v249, v248, v153
	ds_read_b128 v[84:87], v249
	v_add_u32_e32 v251, v248, v154
	ds_read_b128 v[88:91], v251
	v_add_u32_e32 v249, v248, v155
	ds_read_b128 v[92:95], v249
	v_add_u32_e32 v251, v248, v156
	ds_read_b128 v[96:99], v251
	v_add_u32_e32 v249, v248, v157
	ds_read_b128 v[194:197], v249
	v_add_u32_e32 v251, v248, v158
	ds_read_b128 v[198:201], v251
	v_add_u32_e32 v249, v248, v159
	ds_read_b128 v[202:205], v249
	v_add_u32_e32 v251, v248, v160
	ds_read_b128 v[206:209], v251
	s_nop 0
	v_add_u32_e32 v248, s22, v161
	v_mov_b32_e32 v250, v140
	v_add_f32_e32 v243, 0x41000000, v165
	s_waitcnt lgkmcnt(0)
	v_mfma_f32_32x32x16_bf16 v[68:83], v[84:87], v[100:103], v[226:241]
	v_mfma_f32_32x32x16_bf16 v[68:83], v[88:91], v[104:107], v[68:83]
	v_mfma_f32_32x32x16_bf16 v[68:83], v[92:95], v[108:111], v[68:83]
	v_mfma_f32_32x32x16_bf16 v[68:83], v[96:99], v[112:115], v[68:83]
	v_mfma_f32_32x32x16_bf16 v[68:83], v[194:197], v[116:119], v[68:83]
	v_mfma_f32_32x32x16_bf16 v[68:83], v[198:201], v[120:123], v[68:83]
	v_mfma_f32_32x32x16_bf16 v[68:83], v[202:205], v[124:127], v[68:83]
	v_mfma_f32_32x32x16_bf16 v[68:83], v[206:209], v[128:131], v[68:83]
	ds_read_b64_tr_b16 v[84:85], v248 offset:0
	ds_read_b64_tr_b16 v[86:87], v248 offset:2048
	ds_read_b64_tr_b16 v[88:89], v248 offset:4096
	ds_read_b64_tr_b16 v[90:91], v248 offset:6144
	ds_read_b64_tr_b16 v[92:93], v248 offset:512
	ds_read_b64_tr_b16 v[94:95], v248 offset:2560
	ds_read_b64_tr_b16 v[96:97], v248 offset:4608
	ds_read_b64_tr_b16 v[98:99], v248 offset:6656
	ds_read_b64_tr_b16 v[194:195], v248 offset:1024
	ds_read_b64_tr_b16 v[196:197], v248 offset:3072
	ds_read_b64_tr_b16 v[198:199], v248 offset:5120
	ds_read_b64_tr_b16 v[200:201], v248 offset:7168
	ds_read_b64_tr_b16 v[202:203], v248 offset:1536
	ds_read_b64_tr_b16 v[204:205], v248 offset:3584
	ds_read_b64_tr_b16 v[206:207], v248 offset:5632
	ds_read_b64_tr_b16 v[208:209], v248 offset:7680
	s_and_b64 vcc, exec, s[98:99]
	s_cbranch_vccz .Lsel_nm0
	v_cmp_lt_i32_e32 vcc, -1, v163
	v_cmp_lt_i32_e64 s[10:11], 0, v163
	v_cmp_lt_i32_e64 s[12:13], 1, v163
	v_cmp_lt_i32_e64 s[2:3], 2, v163
	s_nop 0
	v_cndmask_b32_e32 v68, v183, v68, vcc
	v_cndmask_b32_e64 v69, v183, v69, s[10:11]
	v_cndmask_b32_e64 v70, v183, v70, s[12:13]
	v_cndmask_b32_e64 v71, v183, v71, s[2:3]
	v_cmp_lt_i32_e32 vcc, 7, v163
	v_cmp_lt_i32_e64 s[10:11], 8, v163
	v_cmp_lt_i32_e64 s[12:13], 9, v163
	v_cmp_lt_i32_e64 s[2:3], 10, v163
	s_nop 0
	v_cndmask_b32_e32 v72, v183, v72, vcc
	v_cndmask_b32_e64 v73, v183, v73, s[10:11]
	v_cndmask_b32_e64 v74, v183, v74, s[12:13]
	v_cndmask_b32_e64 v75, v183, v75, s[2:3]
	v_cmp_lt_i32_e32 vcc, 15, v163
	v_cmp_lt_i32_e64 s[10:11], 16, v163
	v_cmp_lt_i32_e64 s[12:13], 17, v163
	v_cmp_lt_i32_e64 s[2:3], 18, v163
	s_nop 0
	v_cndmask_b32_e32 v76, v183, v76, vcc
	v_cndmask_b32_e64 v77, v183, v77, s[10:11]
	v_cndmask_b32_e64 v78, v183, v78, s[12:13]
	v_cndmask_b32_e64 v79, v183, v79, s[2:3]
	v_cmp_lt_i32_e32 vcc, 23, v163
	v_cmp_lt_i32_e64 s[10:11], 24, v163
	v_cmp_lt_i32_e64 s[12:13], 25, v163
	v_cmp_lt_i32_e64 s[2:3], 26, v163
	s_nop 0
	v_cndmask_b32_e32 v80, v183, v80, vcc
	v_cndmask_b32_e64 v81, v183, v81, s[10:11]
	v_cndmask_b32_e64 v82, v183, v82, s[12:13]
	v_cndmask_b32_e64 v83, v183, v83, s[2:3]
.Lsel_nm0:
	v_max3_f32 v244, v68, v69, v70
	v_max3_f32 v244, v244, v71, v72
	v_max3_f32 v244, v244, v73, v74
	v_max3_f32 v244, v244, v75, v76
	v_max3_f32 v244, v244, v77, v78
	v_max3_f32 v244, v244, v79, v80
	v_max3_f32 v244, v244, v81, v82
	v_max_f32_e32 v244, v244, v83
	v_fmamk_f32 v246, v244, 0x3e0293ee, v250
	v_mov_b32_e32 v245, v246
	s_nop 1
	v_permlane32_swap_b32_e32 v246, v245
	v_max_f32_e32 v246, v246, v245
	v_cmp_gt_f32_e32 vcc, v246, v243
	s_cbranch_vccz .Lsel_nr0
	v_max_f32_e32 v246, v246, v165
	v_sub_f32_e32 v247, v165, v246
	v_exp_f32_e32 v247, v247
	v_mov_b32_e32 v165, v246
	s_and_saveexec_b64 s[2:3], s[8:9]
	ds_write_b32 v147, v247
	s_or_b64 exec, exec, s[2:3]
	v_mul_f32_e32 v162, v162, v247
	ds_read_b128 v[168:171], v146
	ds_read_b128 v[172:175], v146 offset:32
	ds_read_b128 v[242:245], v146 offset:64
	ds_read_b128 v[246:249], v146 offset:96
	s_waitcnt lgkmcnt(0)
	v_mul_f32_e32 v52, v52, v168
	v_mul_f32_e32 v53, v53, v169
	v_mul_f32_e32 v54, v54, v170
	v_mul_f32_e32 v55, v55, v171
	v_mul_f32_e32 v56, v56, v172
	v_mul_f32_e32 v57, v57, v173
	v_mul_f32_e32 v58, v58, v174
	v_mul_f32_e32 v59, v59, v175
	v_mul_f32_e32 v60, v60, v242
	v_mul_f32_e32 v61, v61, v243
	v_mul_f32_e32 v62, v62, v244
	v_mul_f32_e32 v63, v63, v245
	v_mul_f32_e32 v64, v64, v246
	v_mul_f32_e32 v65, v65, v247
	v_mul_f32_e32 v66, v66, v248
	v_mul_f32_e32 v67, v67, v249
	v_mul_f32_e32 v36, v36, v168
	v_mul_f32_e32 v37, v37, v169
	v_mul_f32_e32 v38, v38, v170
	v_mul_f32_e32 v39, v39, v171
	v_mul_f32_e32 v40, v40, v172
	v_mul_f32_e32 v41, v41, v173
	v_mul_f32_e32 v42, v42, v174
	v_mul_f32_e32 v43, v43, v175
	v_mul_f32_e32 v44, v44, v242
	v_mul_f32_e32 v45, v45, v243
	v_mul_f32_e32 v46, v46, v244
	v_mul_f32_e32 v47, v47, v245
	v_mul_f32_e32 v48, v48, v246
	v_mul_f32_e32 v49, v49, v247
	v_mul_f32_e32 v50, v50, v248
	v_mul_f32_e32 v51, v51, v249
	v_mul_f32_e32 v20, v20, v168
	v_mul_f32_e32 v21, v21, v169
	v_mul_f32_e32 v22, v22, v170
	v_mul_f32_e32 v23, v23, v171
	v_mul_f32_e32 v24, v24, v172
	v_mul_f32_e32 v25, v25, v173
	v_mul_f32_e32 v26, v26, v174
	v_mul_f32_e32 v27, v27, v175
	v_mul_f32_e32 v28, v28, v242
	v_mul_f32_e32 v29, v29, v243
	v_mul_f32_e32 v30, v30, v244
	v_mul_f32_e32 v31, v31, v245
	v_mul_f32_e32 v32, v32, v246
	v_mul_f32_e32 v33, v33, v247
	v_mul_f32_e32 v34, v34, v248
	v_mul_f32_e32 v35, v35, v249
	v_mul_f32_e32 v4, v4, v168
	v_mul_f32_e32 v5, v5, v169
	v_mul_f32_e32 v6, v6, v170
	v_mul_f32_e32 v7, v7, v171
	v_mul_f32_e32 v8, v8, v172
	v_mul_f32_e32 v9, v9, v173
	v_mul_f32_e32 v10, v10, v174
	v_mul_f32_e32 v11, v11, v175
	v_mul_f32_e32 v12, v12, v242
	v_mul_f32_e32 v13, v13, v243
	v_mul_f32_e32 v14, v14, v244
	v_mul_f32_e32 v15, v15, v245
	v_mul_f32_e32 v16, v16, v246
	v_mul_f32_e32 v17, v17, v247
	v_mul_f32_e32 v18, v18, v248
	v_mul_f32_e32 v19, v19, v249
; template <int MODE>
; __device__ __forceinline__ void nsa_single(const Params& p, const LaneId& L, int q0, int g, int ntiles, int first, char* smem, const bf16x8* qr, float gate, f32x16* o) {
;     ...
;     NSA_SHALF(0);
;     NSA_SHALF(1);
.Lsel_nr0:
	v_sub_f32_e32 v251, v250, v165
	s_nop 0
	v_fmamk_f32 v68, v68, 0x3e0293ee, v251
	v_fmamk_f32 v69, v69, 0x3e0293ee, v251
	v_fmamk_f32 v70, v70, 0x3e0293ee, v251
	v_fmamk_f32 v71, v71, 0x3e0293ee, v251
	v_fmamk_f32 v72, v72, 0x3e0293ee, v251
	v_fmamk_f32 v73, v73, 0x3e0293ee, v251
	v_fmamk_f32 v74, v74, 0x3e0293ee, v251
	v_fmamk_f32 v75, v75, 0x3e0293ee, v251
	v_fmamk_f32 v76, v76, 0x3e0293ee, v251
	v_fmamk_f32 v77, v77, 0x3e0293ee, v251
	v_fmamk_f32 v78, v78, 0x3e0293ee, v251
	v_fmamk_f32 v79, v79, 0x3e0293ee, v251
	v_fmamk_f32 v80, v80, 0x3e0293ee, v251
	v_fmamk_f32 v81, v81, 0x3e0293ee, v251
	v_fmamk_f32 v82, v82, 0x3e0293ee, v251
	v_fmamk_f32 v83, v83, 0x3e0293ee, v251
	v_exp_f32_e32 v68, v68
	v_exp_f32_e32 v69, v69
	v_exp_f32_e32 v70, v70
	v_exp_f32_e32 v71, v71
	v_exp_f32_e32 v72, v72
	v_exp_f32_e32 v73, v73
	v_exp_f32_e32 v74, v74
	v_exp_f32_e32 v75, v75
	v_exp_f32_e32 v76, v76
	v_exp_f32_e32 v77, v77
	v_exp_f32_e32 v78, v78
	v_exp_f32_e32 v79, v79
	v_exp_f32_e32 v80, v80
	v_exp_f32_e32 v81, v81
	v_exp_f32_e32 v82, v82
	v_exp_f32_e32 v83, v83
	s_nop 0
	v_add_f32_e32 v246, v68, v69
	v_add_f32_e32 v247, v70, v71
	v_add_f32_e32 v246, v246, v72
	v_add_f32_e32 v246, v246, v73
	v_add_f32_e32 v247, v247, v74
	v_add_f32_e32 v247, v247, v75
	v_add_f32_e32 v246, v246, v76
	v_add_f32_e32 v246, v246, v77
	v_add_f32_e32 v247, v247, v78
	v_add_f32_e32 v247, v247, v79
	v_add_f32_e32 v246, v246, v80
	v_add_f32_e32 v246, v246, v81
	v_add_f32_e32 v247, v247, v82
	v_add_f32_e32 v247, v247, v83
	v_add_f32_e32 v246, v246, v247
	v_add_f32_e32 v162, v162, v246
	v_cvt_pk_bf16_f32 v168, v68, v69
	v_cvt_pk_bf16_f32 v169, v70, v71
	v_cvt_pk_bf16_f32 v170, v72, v73
	v_cvt_pk_bf16_f32 v171, v74, v75
	v_cvt_pk_bf16_f32 v172, v76, v77
	v_cvt_pk_bf16_f32 v173, v78, v79
	v_cvt_pk_bf16_f32 v174, v80, v81
	v_cvt_pk_bf16_f32 v175, v82, v83
	s_waitcnt lgkmcnt(0)
	s_nop 1
	v_permlane32_swap_b32_e32 v168, v170
	v_permlane32_swap_b32_e32 v169, v171
	v_permlane32_swap_b32_e32 v172, v174
	v_permlane32_swap_b32_e32 v173, v175
	s_nop 1
	v_mfma_f32_32x32x16_bf16 v[52:67], v[168:171], v[84:87], v[52:67]
	v_mfma_f32_32x32x16_bf16 v[36:51], v[168:171], v[92:95], v[36:51]
	v_mfma_f32_32x32x16_bf16 v[20:35], v[168:171], v[194:197], v[20:35]
	v_mfma_f32_32x32x16_bf16 v[4:19], v[168:171], v[202:205], v[4:19]
	v_mfma_f32_32x32x16_bf16 v[52:67], v[172:175], v[88:91], v[52:67]
	v_mfma_f32_32x32x16_bf16 v[36:51], v[172:175], v[96:99], v[36:51]
	v_mfma_f32_32x32x16_bf16 v[20:35], v[172:175], v[198:201], v[20:35]
	v_mfma_f32_32x32x16_bf16 v[4:19], v[172:175], v[206:209], v[4:19]
	v_add_u32_e32 v248, s22, v152
	v_add_u32_e32 v249, v248, v153
	ds_read_b128 v[84:87], v249 offset:8192
	v_add_u32_e32 v251, v248, v154
	ds_read_b128 v[88:91], v251 offset:8192
	v_add_u32_e32 v249, v248, v155
	ds_read_b128 v[92:95], v249 offset:8192
	v_add_u32_e32 v251, v248, v156
	ds_read_b128 v[96:99], v251 offset:8192
	v_add_u32_e32 v249, v248, v157
	ds_read_b128 v[194:197], v249 offset:8192
	v_add_u32_e32 v251, v248, v158
	ds_read_b128 v[198:201], v251 offset:8192
	v_add_u32_e32 v249, v248, v159
	ds_read_b128 v[202:205], v249 offset:8192
	v_add_u32_e32 v251, v248, v160
	ds_read_b128 v[206:209], v251 offset:8192
	s_nop 0
	v_add_u32_e32 v248, s22, v161
	v_fmamk_f32 v250, v138, 0x42000000, v140
	v_add_f32_e32 v243, 0x41000000, v165
	s_waitcnt lgkmcnt(0)
	v_mfma_f32_32x32x16_bf16 v[68:83], v[84:87], v[100:103], v[226:241]
	v_mfma_f32_32x32x16_bf16 v[68:83], v[88:91], v[104:107], v[68:83]
	v_mfma_f32_32x32x16_bf16 v[68:83], v[92:95], v[108:111], v[68:83]
	v_mfma_f32_32x32x16_bf16 v[68:83], v[96:99], v[112:115], v[68:83]
	v_mfma_f32_32x32x16_bf16 v[68:83], v[194:197], v[116:119], v[68:83]
	v_mfma_f32_32x32x16_bf16 v[68:83], v[198:201], v[120:123], v[68:83]
	v_mfma_f32_32x32x16_bf16 v[68:83], v[202:205], v[124:127], v[68:83]
	v_mfma_f32_32x32x16_bf16 v[68:83], v[206:209], v[128:131], v[68:83]
	ds_read_b64_tr_b16 v[84:85], v248 offset:8192
	ds_read_b64_tr_b16 v[86:87], v248 offset:10240
	ds_read_b64_tr_b16 v[88:89], v248 offset:12288
	ds_read_b64_tr_b16 v[90:91], v248 offset:14336
	ds_read_b64_tr_b16 v[92:93], v248 offset:8704
	ds_read_b64_tr_b16 v[94:95], v248 offset:10752
	ds_read_b64_tr_b16 v[96:97], v248 offset:12800
	ds_read_b64_tr_b16 v[98:99], v248 offset:14848
	ds_read_b64_tr_b16 v[194:195], v248 offset:9216
	ds_read_b64_tr_b16 v[196:197], v248 offset:11264
	ds_read_b64_tr_b16 v[198:199], v248 offset:13312
	ds_read_b64_tr_b16 v[200:201], v248 offset:15360
	ds_read_b64_tr_b16 v[202:203], v248 offset:9728
	ds_read_b64_tr_b16 v[204:205], v248 offset:11776
	ds_read_b64_tr_b16 v[206:207], v248 offset:13824
	ds_read_b64_tr_b16 v[208:209], v248 offset:15872
	s_and_b64 vcc, exec, s[98:99]
	s_cbranch_vccz .Lsel_nm1
	v_cmp_lt_i32_e32 vcc, 31, v163
	v_cmp_lt_i32_e64 s[10:11], 32, v163
	v_cmp_lt_i32_e64 s[12:13], 33, v163
	v_cmp_lt_i32_e64 s[2:3], 34, v163
	s_nop 0
	v_cndmask_b32_e32 v68, v183, v68, vcc
	v_cndmask_b32_e64 v69, v183, v69, s[10:11]
	v_cndmask_b32_e64 v70, v183, v70, s[12:13]
	v_cndmask_b32_e64 v71, v183, v71, s[2:3]
	v_cmp_lt_i32_e32 vcc, 39, v163
	v_cmp_lt_i32_e64 s[10:11], 40, v163
	v_cmp_lt_i32_e64 s[12:13], 41, v163
	v_cmp_lt_i32_e64 s[2:3], 42, v163
	s_nop 0
	v_cndmask_b32_e32 v72, v183, v72, vcc
	v_cndmask_b32_e64 v73, v183, v73, s[10:11]
	v_cndmask_b32_e64 v74, v183, v74, s[12:13]
	v_cndmask_b32_e64 v75, v183, v75, s[2:3]
	v_cmp_lt_i32_e32 vcc, 47, v163
	v_cmp_lt_i32_e64 s[10:11], 48, v163
	v_cmp_lt_i32_e64 s[12:13], 49, v163
	v_cmp_lt_i32_e64 s[2:3], 50, v163
	s_nop 0
	v_cndmask_b32_e32 v76, v183, v76, vcc
	v_cndmask_b32_e64 v77, v183, v77, s[10:11]
	v_cndmask_b32_e64 v78, v183, v78, s[12:13]
	v_cndmask_b32_e64 v79, v183, v79, s[2:3]
	v_cmp_lt_i32_e32 vcc, 55, v163
	v_cmp_lt_i32_e64 s[10:11], 56, v163
	v_cmp_lt_i32_e64 s[12:13], 57, v163
	v_cmp_lt_i32_e64 s[2:3], 58, v163
	s_nop 0
	v_cndmask_b32_e32 v80, v183, v80, vcc
	v_cndmask_b32_e64 v81, v183, v81, s[10:11]
	v_cndmask_b32_e64 v82, v183, v82, s[12:13]
	v_cndmask_b32_e64 v83, v183, v83, s[2:3]

; template <int MODE>
; __device__ __forceinline__ void nsa_single(const Params& p, const LaneId& L, int q0, int g, int ntiles, int first, char* smem, const bf16x8* qr, float gate, f32x16* o) {
;     ...
;   for (int i = 0; i < ntiles; ++i) {
;     const int row = tile_row(i), buf = i & 1;
;     ...
;     NSA_SHALF(0);
;     NSA_SHALF(1);
;     ...
;   }
.Lsel_nr1:
	v_sub_f32_e32 v251, v250, v165
	s_nop 0
	v_fmamk_f32 v68, v68, 0x3e0293ee, v251
	v_fmamk_f32 v69, v69, 0x3e0293ee, v251
	v_fmamk_f32 v70, v70, 0x3e0293ee, v251
	v_fmamk_f32 v71, v71, 0x3e0293ee, v251
	v_fmamk_f32 v72, v72, 0x3e0293ee, v251
	v_fmamk_f32 v73, v73, 0x3e0293ee, v251
	v_fmamk_f32 v74, v74, 0x3e0293ee, v251
	v_fmamk_f32 v75, v75, 0x3e0293ee, v251
	v_fmamk_f32 v76, v76, 0x3e0293ee, v251
	v_fmamk_f32 v77, v77, 0x3e0293ee, v251
	v_fmamk_f32 v78, v78, 0x3e0293ee, v251
	v_fmamk_f32 v79, v79, 0x3e0293ee, v251
	v_fmamk_f32 v80, v80, 0x3e0293ee, v251
	v_fmamk_f32 v81, v81, 0x3e0293ee, v251
	v_fmamk_f32 v82, v82, 0x3e0293ee, v251
	v_fmamk_f32 v83, v83, 0x3e0293ee, v251
	v_exp_f32_e32 v68, v68
	v_exp_f32_e32 v69, v69
	v_exp_f32_e32 v70, v70
	v_exp_f32_e32 v71, v71
	v_exp_f32_e32 v72, v72
	v_exp_f32_e32 v73, v73
	v_exp_f32_e32 v74, v74
	v_exp_f32_e32 v75, v75
	v_exp_f32_e32 v76, v76
	v_exp_f32_e32 v77, v77
	v_exp_f32_e32 v78, v78
	v_exp_f32_e32 v79, v79
	v_exp_f32_e32 v80, v80
	v_exp_f32_e32 v81, v81
	v_exp_f32_e32 v82, v82
	v_exp_f32_e32 v83, v83
	s_nop 0
	v_add_f32_e32 v246, v68, v69
	v_add_f32_e32 v247, v70, v71
	v_add_f32_e32 v246, v246, v72
	v_add_f32_e32 v246, v246, v73
	v_add_f32_e32 v247, v247, v74
	v_add_f32_e32 v247, v247, v75
	v_add_f32_e32 v246, v246, v76
	v_add_f32_e32 v246, v246, v77
	v_add_f32_e32 v247, v247, v78
	v_add_f32_e32 v247, v247, v79
	v_add_f32_e32 v246, v246, v80
	v_add_f32_e32 v246, v246, v81
	v_add_f32_e32 v247, v247, v82
	v_add_f32_e32 v247, v247, v83
	v_add_f32_e32 v246, v246, v247
	v_add_f32_e32 v162, v162, v246
	v_cvt_pk_bf16_f32 v168, v68, v69
	v_cvt_pk_bf16_f32 v169, v70, v71
	v_cvt_pk_bf16_f32 v170, v72, v73
	v_cvt_pk_bf16_f32 v171, v74, v75
	v_cvt_pk_bf16_f32 v172, v76, v77
	v_cvt_pk_bf16_f32 v173, v78, v79
	v_cvt_pk_bf16_f32 v174, v80, v81
	v_cvt_pk_bf16_f32 v175, v82, v83
	s_waitcnt lgkmcnt(0)
	s_nop 1
	v_permlane32_swap_b32_e32 v168, v170
	v_permlane32_swap_b32_e32 v169, v171
	v_permlane32_swap_b32_e32 v172, v174
	v_permlane32_swap_b32_e32 v173, v175
	s_nop 1
	v_mfma_f32_32x32x16_bf16 v[52:67], v[168:171], v[84:87], v[52:67]
	v_mfma_f32_32x32x16_bf16 v[36:51], v[168:171], v[92:95], v[36:51]
	v_mfma_f32_32x32x16_bf16 v[20:35], v[168:171], v[194:197], v[20:35]
	v_mfma_f32_32x32x16_bf16 v[4:19], v[168:171], v[202:205], v[4:19]
	v_mfma_f32_32x32x16_bf16 v[52:67], v[172:175], v[88:91], v[52:67]
	v_mfma_f32_32x32x16_bf16 v[36:51], v[172:175], v[96:99], v[36:51]
	v_mfma_f32_32x32x16_bf16 v[20:35], v[172:175], v[198:201], v[20:35]
	v_mfma_f32_32x32x16_bf16 v[4:19], v[172:175], v[206:209], v[4:19]
	s_add_i32 s26, s26, -1
	s_add_i32 s61, s61, 1
	s_addk_i32 s97, 0x4000
	s_cmp_eq_u32 s26, 0
	s_cbranch_scc1 .LBB0_335
	s_branch .LBB0_316

; __global__ void __launch_bounds__(NTHR) mega(Params p) {
	.amdhsa_kernel _Z4mega6Params
		.amdhsa_group_segment_fixed_size 139264
		.amdhsa_private_segment_fixed_size 0
		.amdhsa_kernarg_size 560
		.amdhsa_user_sgpr_count 2
		.amdhsa_user_sgpr_dispatch_ptr 0
		.amdhsa_user_sgpr_queue_ptr 0
		.amdhsa_user_sgpr_kernarg_segment_ptr 1
		.amdhsa_user_sgpr_dispatch_id 0
		.amdhsa_user_sgpr_kernarg_preload_length 0
		.amdhsa_user_sgpr_kernarg_preload_offset 0
		.amdhsa_user_sgpr_private_segment_size 0
		.amdhsa_uses_dynamic_stack 0
		.amdhsa_enable_private_segment 0
		.amdhsa_system_sgpr_workgroup_id_x 1
		.amdhsa_system_sgpr_workgroup_id_y 0
		.amdhsa_system_sgpr_workgroup_id_z 0
		.amdhsa_system_sgpr_workgroup_info 0
		.amdhsa_system_vgpr_workitem_id 2
		.amdhsa_next_free_vgpr 253
		.amdhsa_next_free_sgpr 102
		.amdhsa_accum_offset 256
		.amdhsa_reserve_vcc 1
		.amdhsa_float_round_mode_32 0
		.amdhsa_float_round_mode_16_64 0
		.amdhsa_float_denorm_mode_32 3
		.amdhsa_float_denorm_mode_16_64 3
		.amdhsa_dx10_clamp 1
		.amdhsa_ieee_mode 1
		.amdhsa_fp16_overflow 0
		.amdhsa_tg_split 0
		.amdhsa_exception_fp_ieee_invalid_op 0
		.amdhsa_exception_fp_denorm_src 0
		.amdhsa_exception_fp_ieee_div_zero 0
		.amdhsa_exception_fp_ieee_overflow 0
		.amdhsa_exception_fp_ieee_underflow 0
		.amdhsa_exception_fp_ieee_inexact 0
		.amdhsa_exception_int_div_zero 0
	.end_amdhsa_kernel

; __global__ void __launch_bounds__(NTHR) mega(Params p) {
amdhsa.kernels:
  - .agpr_count:     0
    .args:
      - .offset:         0
        .size:           304
        .value_kind:     by_value
      - .offset:         304
        .size:           4
        .value_kind:     hidden_block_count_x
      - .offset:         308
        .size:           4
        .value_kind:     hidden_block_count_y
      - .offset:         312
        .size:           4
        .value_kind:     hidden_block_count_z
      - .offset:         316
        .size:           2
        .value_kind:     hidden_group_size_x
      - .offset:         318
        .size:           2
        .value_kind:     hidden_group_size_y
      - .offset:         320
        .size:           2
        .value_kind:     hidden_group_size_z
      - .offset:         322
        .size:           2
        .value_kind:     hidden_remainder_x
      - .offset:         324
        .size:           2
        .value_kind:     hidden_remainder_y
      - .offset:         326
        .size:           2
        .value_kind:     hidden_remainder_z
      - .offset:         344
        .size:           8
        .value_kind:     hidden_global_offset_x
      - .offset:         352
        .size:           8
        .value_kind:     hidden_global_offset_y
      - .offset:         360
        .size:           8
        .value_kind:     hidden_global_offset_z
      - .offset:         368
        .size:           2
        .value_kind:     hidden_grid_dims
      - .offset:         392
        .size:           8
        .value_kind:     hidden_multigrid_sync_arg
    .group_segment_fixed_size: 139264
    .kernarg_segment_align: 8
    .kernarg_segment_size: 560
    .language:       OpenCL C
    .language_version:
      - 2
      - 0
    .max_flat_workgroup_size: 512
    .name:           _Z4mega6Params
    .private_segment_fixed_size: 0
    .sgpr_count:     108
    .sgpr_spill_count: 55
    .symbol:         _Z4mega6Params.kd
    .uniform_work_group_size: 1
    .uses_dynamic_stack: false
    .vgpr_count:     253
    .vgpr_spill_count: 0
    .wavefront_size: 64
